# grid barrier: only the first workgroup of each CU (census role 0) and the XCD leaders issue the L1 invalidate
# speedup vs baseline: 1.0070x; 1.0070x over previous
; __device__ __forceinline__ unsigned xb_ld(unsigned* p) { return __hip_atomic_load(p, __ATOMIC_RELAXED, __HIP_MEMORY_SCOPE_AGENT); }
; __device__ __forceinline__ unsigned xb_add(unsigned* p, unsigned v) { return __hip_atomic_fetch_add(p, v, __ATOMIC_RELAXED, __HIP_MEMORY_SCOPE_AGENT); }
; #define XB_SPIN(cond, bar) do { unsigned _sp = 0; while (cond) { __builtin_amdgcn_s_sleep(0); \
;     if ((++_sp & 255u) == 0u) { if (xb_ld(&(bar)[XB_TMO])) break; if (_sp > XB_SPIN_CAP) { atomicAdd(&(bar)[XB_TMO], 1u); break; } } } } while (0)
; __device__ __forceinline__ void xcd_barrier(XcdBarrier& b, const int tid, const unsigned G) {
;     ...
;     const unsigned nloc = b.nloc, nx = b.nx;
;     const unsigned old = xb_add(&bar[XB_XSUB(b.x)], 1u);
;     const unsigned gen = old / nloc;
;     if (old + 1u == (gen + 1u) * nloc) {
;       __builtin_amdgcn_fence(__ATOMIC_RELEASE, "agent");
;       asm volatile("s_waitcnt vmcnt(0)" ::: "memory");
;       const unsigned og = xb_add(&bar[XB_TOP], 1u);
;       const unsigned tg = og / nx;
;       if (og + 1u == (tg + 1u) * nx) xb_add(&bar[XB_TOPGEN], 1u);
;       else XB_SPIN(xb_ld(&bar[XB_TOPGEN]) == tg, bar);
;       __builtin_amdgcn_fence(__ATOMIC_ACQUIRE, "agent");
;       xb_add(&bar[XB_XGEN(b.x)], 1u);
;       asm volatile("s_waitcnt vmcnt(0)" ::: "memory");
;     } else {
;       XB_SPIN(xb_ld(&bar[XB_XGEN(b.x)]) == gen, bar);
;       __builtin_amdgcn_fence(__ATOMIC_ACQUIRE, "agent");
;       asm volatile("s_waitcnt vmcnt(0)" ::: "memory");
.LBB0_50:
	s_or_b64 exec, exec, s[34:35]
	s_waitcnt vmcnt(0)
	v_readfirstlane_b32 s23, v1
	v_sub_u32_e32 v2, 0, v126
	s_nop 0
	v_add_u32_e32 v1, s23, v0
	v_cvt_f32_u32_e32 v0, v126
	v_rcp_iflag_f32_e32 v0, v0
	s_nop 0
	v_mul_f32_e32 v0, 0x4f7ffffe, v0
	v_cvt_u32_f32_e32 v0, v0
	v_mul_lo_u32 v2, v2, v0
	v_mul_hi_u32 v2, v0, v2
	v_add_u32_e32 v0, v0, v2
	v_mul_hi_u32 v0, v1, v0
	v_mul_lo_u32 v2, v0, v126
	v_sub_u32_e32 v2, v1, v2
	v_cmp_ge_u32_e32 vcc, v2, v126
	v_add_u32_e32 v4, 1, v0
	v_add_u32_e32 v1, 1, v1
	v_cndmask_b32_e32 v0, v0, v4, vcc
	v_sub_u32_e32 v4, v2, v126
	v_cndmask_b32_e32 v2, v2, v4, vcc
	v_cmp_ge_u32_e32 vcc, v2, v126
	v_add_u32_e32 v2, 1, v0
	s_nop 0
	v_cndmask_b32_e32 v0, v0, v2, vcc
	v_mad_u64_u32 v[4:5], s[24:25], v126, v0, v[126:127]
	v_cmp_ne_u32_e32 vcc, v1, v4
	v_add_u32_e32 v2, 1, v0
	v_mul_lo_u32 v2, v2, v128
	v_readlane_b32 s24, v253, 13
	v_readlane_b32 s25, v253, 14
	v_readlane_b32 s23, v252, 2
	s_nop 4
	s_cbranch_vccnz .Lxb_wait
	buffer_wbl2 sc1
	s_waitcnt vmcnt(0)
	global_atomic_add v3, v129, s[24:25]
	s_branch .Lxb_inv
.Lxb_wait:
	s_cmp_lg_u32 s23, 0
	s_cbranch_scc1 .Lxb_spin
